# early V-fragment reads also in the general softmax path (DIAG / NEAR / STR128 tiles)
# baseline (speedup 1.0000x reference)
; __device__ __forceinline__ void partialSM(f32x16& p0, f32x16& p1, float& m_reg, float& mn, float& alpha) {
;     float pmax = p0[0];
; #pragma unroll
;     for (int r = 1; r < 16; ++r) pmax = fmaxf(pmax, p0[r]);
; #pragma unroll
;     for (int r = 0; r < 16; ++r) pmax = fmaxf(pmax, p1[r]);
;     { auto rr = __builtin_amdgcn_permlane32_swap(__float_as_uint(pmax), __float_as_uint(pmax), false, false);
;       pmax = fmaxf(__uint_as_float(rr[0]), __uint_as_float(rr[1])); }
;     constexpr float C2 = LOG2E * SCALE;
;     if (__builtin_expect(__all((pmax - m_reg) * SCALE <= THR), 1)) { mn = m_reg; alpha = 1.f; }
;     else { mn = fmaxf(m_reg, pmax); alpha = __builtin_amdgcn_exp2f((m_reg - mn) * C2); m_reg = mn; }
;     const float mnL = -mn * C2;
; #pragma unroll
;     for (int r = 0; r < 16; ++r) p0[r] = __builtin_fmaf(p0[r], C2, mnL);
; #pragma unroll
;     for (int r = 0; r < 16; ++r) p1[r] = __builtin_fmaf(p1[r], C2, mnL);
; #pragma unroll
;     for (int r = 0; r < 16; ++r) p0[r] = __builtin_amdgcn_exp2f(p0[r]);
; #pragma unroll
;     for (int r = 0; r < 16; ++r) p1[r] = __builtin_amdgcn_exp2f(p1[r]);
; }
; __device__ __forceinline__ void pack_p(const f32x16& p0, const f32x16& p1, bf16x8& pa0, bf16x8& pa1, bf16x8& pa2, bf16x8& pa3) {
;     FA_PK4(p0, 0, pa0); FA_PK4(p0, 8, pa1); FA_PK4(p1, 0, pa2); FA_PK4(p1, 8, pa3);
; }
; __device__ __forceinline__ void finishSM(f32x16& p0, f32x16& p1, float alpha, float& l_reg, bf16x8& pa0, bf16x8& pa1, bf16x8& pa2, bf16x8& pa3) {
;     float ps = 0;
; #pragma unroll
;     for (int r = 0; r < 16; ++r) ps += p0[r];
; #pragma unroll
;     for (int r = 0; r < 16; ++r) ps += p1[r];
;     { auto rr = __builtin_amdgcn_permlane32_swap(__float_as_uint(ps), __float_as_uint(ps), false, false);
;       ps = __uint_as_float(rr[0]) + __uint_as_float(rr[1]); }
;     l_reg = l_reg * alpha + ps;
;     pack_p(p0, p1, pa0, pa1, pa2, pa3);
; }
.LBB0_333:
	v_add_u32_e32 v96, s56, v231
	ds_read_b64_tr_b16 v[80:81], v96 offset:0x0
	ds_read_b64_tr_b16 v[82:83], v96 offset:0x800
	ds_read_b64_tr_b16 v[84:85], v96 offset:0x1000
	ds_read_b64_tr_b16 v[86:87], v96 offset:0x1800
	ds_read_b64_tr_b16 v[88:89], v96 offset:0x2000
	ds_read_b64_tr_b16 v[90:91], v96 offset:0x2800
	ds_read_b64_tr_b16 v[92:93], v96 offset:0x3000
	ds_read_b64_tr_b16 v[94:95], v96 offset:0x3800
	v_max_f32_e32 v0, v113, v113
	v_max_f32_e32 v2, v112, v112
	v_max_f32_e32 v0, v2, v0
	v_max3_f32 v0, v0, v114, v115
	v_max3_f32 v0, v0, v116, v117
	v_max3_f32 v0, v0, v118, v119
	v_max3_f32 v0, v0, v120, v121
	v_max3_f32 v0, v0, v122, v123
	v_max3_f32 v0, v0, v124, v125
	v_max3_f32 v0, v0, v126, v127
	v_max3_f32 v0, v0, v128, v129
	v_max3_f32 v0, v0, v130, v131
	v_max3_f32 v0, v0, v132, v133
	v_max3_f32 v0, v0, v134, v135
	v_max3_f32 v0, v0, v136, v137
	v_max3_f32 v0, v0, v138, v139
	v_max3_f32 v0, v0, v140, v141
	v_max3_f32 v0, v0, v142, v143
	v_mov_b32_e32 v2, v0
	s_nop 1
	v_permlane32_swap_b32_e32 v0, v2
	v_max_f32_e32 v2, v2, v2
	v_max_f32_e32 v0, v0, v0
	v_max_f32_e32 v0, v0, v2
	v_sub_f32_e32 v2, v0, v234
	v_mul_f32_e32 v2, 0x3db504f3, v2
	v_cmp_ge_f32_e32 vcc, s58, v2
	v_max_f32_e32 v2, v234, v234
	v_max_f32_e32 v0, v2, v0
	v_sub_f32_e32 v2, v234, v0
	v_mul_f32_e32 v2, 0x3e0293ee, v2
	v_exp_f32_e32 v2, v2
	s_cmp_eq_u64 vcc, exec
	s_cselect_b64 vcc, -1, 0
	v_cndmask_b32_e32 v14, v0, v234, vcc
	v_mul_f32_e32 v0, 0xbe0293ee, v14
	v_cndmask_b32_e64 v235, v2, 1.0, vcc
	v_fmamk_f32 v2, v112, 0x3e0293ee, v0
	v_fmamk_f32 v3, v113, 0x3e0293ee, v0
	v_exp_f32_e32 v2, v2
	v_fmamk_f32 v4, v114, 0x3e0293ee, v0
	v_exp_f32_e32 v3, v3
	v_fmamk_f32 v5, v115, 0x3e0293ee, v0
	v_exp_f32_e32 v4, v4
	v_fmamk_f32 v6, v116, 0x3e0293ee, v0
	v_fmamk_f32 v15, v124, 0x3e0293ee, v0
	v_exp_f32_e32 v5, v5
	v_fmamk_f32 v7, v117, 0x3e0293ee, v0
	v_fmamk_f32 v117, v130, 0x3e0293ee, v0
	v_exp_f32_e32 v6, v6
	v_exp_f32_e32 v130, v15
	v_add_f32_e32 v15, 0, v2
	v_fmamk_f32 v8, v118, 0x3e0293ee, v0
	v_exp_f32_e32 v7, v7
	v_add_f32_e32 v15, v3, v15
	v_fmamk_f32 v9, v119, 0x3e0293ee, v0
	v_exp_f32_e32 v8, v8
	v_add_f32_e32 v15, v4, v15
	v_fmamk_f32 v10, v120, 0x3e0293ee, v0
	v_exp_f32_e32 v9, v9
	v_add_f32_e32 v15, v5, v15
	v_fmamk_f32 v11, v121, 0x3e0293ee, v0
	v_exp_f32_e32 v10, v10
	v_add_f32_e32 v15, v6, v15
	v_fmamk_f32 v12, v122, 0x3e0293ee, v0
	v_exp_f32_e32 v11, v11
	v_add_f32_e32 v15, v7, v15
	v_fmamk_f32 v13, v123, 0x3e0293ee, v0
	v_exp_f32_e32 v12, v12
	v_add_f32_e32 v15, v8, v15
	v_exp_f32_e32 v13, v13
	v_add_f32_e32 v15, v9, v15
	v_fmamk_f32 v112, v125, 0x3e0293ee, v0
	v_add_f32_e32 v15, v10, v15
	v_fmamk_f32 v113, v126, 0x3e0293ee, v0
	v_exp_f32_e32 v112, v112
	v_add_f32_e32 v15, v11, v15
	v_fmamk_f32 v114, v127, 0x3e0293ee, v0
	v_exp_f32_e32 v113, v113
	v_add_f32_e32 v15, v12, v15
	v_fmamk_f32 v115, v128, 0x3e0293ee, v0
	v_exp_f32_e32 v114, v114
	v_add_f32_e32 v15, v13, v15
	v_fmamk_f32 v116, v129, 0x3e0293ee, v0
	v_exp_f32_e32 v115, v115
	v_add_f32_e32 v15, v130, v15
	v_exp_f32_e32 v116, v116
	v_add_f32_e32 v15, v112, v15
	v_fmamk_f32 v118, v131, 0x3e0293ee, v0
	v_exp_f32_e32 v117, v117
	v_add_f32_e32 v15, v113, v15
	v_fmamk_f32 v119, v132, 0x3e0293ee, v0
	v_exp_f32_e32 v118, v118
	v_add_f32_e32 v15, v114, v15
	v_fmamk_f32 v120, v133, 0x3e0293ee, v0
	v_exp_f32_e32 v119, v119
	v_add_f32_e32 v15, v115, v15
	v_fmamk_f32 v121, v134, 0x3e0293ee, v0
	v_exp_f32_e32 v120, v120
	v_add_f32_e32 v15, v116, v15
	v_fmamk_f32 v122, v135, 0x3e0293ee, v0
	v_exp_f32_e32 v121, v121
	v_add_f32_e32 v15, v117, v15
	v_fmamk_f32 v123, v136, 0x3e0293ee, v0
	v_exp_f32_e32 v122, v122
	v_add_f32_e32 v15, v118, v15
	v_fmamk_f32 v124, v137, 0x3e0293ee, v0
	v_exp_f32_e32 v123, v123
	v_add_f32_e32 v15, v119, v15
	v_fmamk_f32 v125, v138, 0x3e0293ee, v0
	v_exp_f32_e32 v124, v124
	v_add_f32_e32 v15, v120, v15
	v_fmamk_f32 v126, v139, 0x3e0293ee, v0
	v_exp_f32_e32 v125, v125
	v_add_f32_e32 v15, v121, v15
	v_fmamk_f32 v127, v140, 0x3e0293ee, v0
	v_exp_f32_e32 v126, v126
	v_add_f32_e32 v15, v122, v15
	v_fmamk_f32 v128, v141, 0x3e0293ee, v0
	v_exp_f32_e32 v127, v127
	v_add_f32_e32 v15, v123, v15
	v_fmamk_f32 v129, v142, 0x3e0293ee, v0
	v_exp_f32_e32 v128, v128
	v_add_f32_e32 v15, v124, v15
	v_fmac_f32_e32 v0, 0x3e0293ee, v143
	v_exp_f32_e32 v129, v129
	v_add_f32_e32 v15, v125, v15
	v_exp_f32_e32 v0, v0
	v_add_f32_e32 v15, v126, v15
	v_add_f32_e32 v15, v127, v15
	v_add_f32_e32 v15, v128, v15
	v_add_f32_e32 v15, v129, v15
	v_add_f32_e32 v15, v0, v15
	v_mov_b32_e32 v131, v15
	s_nop 1
	v_permlane32_swap_b32_e32 v15, v131
	v_add_f32_e32 v15, v15, v131
	v_cvt_pk_bf16_f32 v2, v2, v3
	v_cvt_pk_bf16_f32 v3, v4, v5
	v_cvt_pk_bf16_f32 v4, v6, v7
	v_cvt_pk_bf16_f32 v5, v8, v9
	v_cvt_pk_bf16_f32 v6, v10, v11
	v_cvt_pk_bf16_f32 v7, v12, v13
	v_cvt_pk_bf16_f32 v8, v130, v112
	v_cvt_pk_bf16_f32 v9, v113, v114
	v_cvt_pk_bf16_f32 v10, v115, v116
	v_cvt_pk_bf16_f32 v11, v117, v118
	v_cvt_pk_bf16_f32 v12, v119, v120
	v_cvt_pk_bf16_f32 v13, v121, v122
	v_cvt_pk_bf16_f32 v112, v123, v124
	v_cvt_pk_bf16_f32 v113, v125, v126
	v_cvt_pk_bf16_f32 v114, v127, v128
	v_cvt_pk_bf16_f32 v115, v129, v0
	v_fmac_f32_e32 v15, v233, v235
	v_permlane32_swap_b32_e32 v2, v4
	v_permlane32_swap_b32_e32 v3, v5
	v_permlane32_swap_b32_e32 v6, v8
	v_permlane32_swap_b32_e32 v7, v9
	v_permlane32_swap_b32_e32 v10, v12
	v_permlane32_swap_b32_e32 v11, v13
	v_permlane32_swap_b32_e32 v112, v114
	v_permlane32_swap_b32_e32 v113, v115
	v_add_u32_e32 v0, s56, v231
	v_cmp_gt_f32_e32 vcc, 1.0, v235
	s_cbranch_vccnz .LBB0_335
	s_branch .Lpv_reads_done
